# ret_pass2 epilogue: the four gain/bias vector pairs per head loaded together with one wait (was load-pair -> vmcnt(0) four times, each also waiting for the previous output store)
# speedup vs baseline: 1.0183x; 1.0062x over previous
; DI float bperm(float v, int srclane) { return __int_as_float(__builtin_amdgcn_ds_bpermute(srclane << 2, __float_as_int(v))); }
; DI f32x4 bf4_to_f32(const u32x2 v) { return (f32x4){__uint_as_float(v.x << 16), __uint_as_float(v.x & 0xffff0000u), __uint_as_float(v.y << 16), __uint_as_float(v.y & 0xffff0000u)}; }
; DI void ret_pass2(LAS unsigned char* lds, const Args& a, const LayerP& P, int unit, int wv) {
;     ...
;         wgemm<4, 1>(cacc, STt, PQ, Qs + i0 * PQ, PQ, 64, lane);
;         { const int i = i0 + r; const float qd = __expf(lg * (float)(i + 1)); f32x4 o[4]; float s = 0.f;
; #pragma unroll
;           for (int mi = 0; mi < 4; ++mi) { o[mi] = oacc[mi][0] + cacc[mi][0] * qd; s += (o[mi][0] + o[mi][1]) + (o[mi][2] + o[mi][3]); }
;           s += bperm(s, lane ^ 16); s += bperm(s, lane ^ 32);
;           const float mu = s * (1.0f / 64.0f); float v2 = 0.f;
; #pragma unroll
;           for (int mi = 0; mi < 4; ++mi) { o[mi] = o[mi] - mu; v2 += (o[mi][0] * o[mi][0] + o[mi][1] * o[mi][1]) + (o[mi][2] * o[mi][2] + o[mi][3] * o[mi][3]); }
;           v2 += bperm(v2, lane ^ 16); v2 += bperm(v2, lane ^ 32);
;           const float rs = __builtin_amdgcn_rsqf(v2 * (1.0f / 64.0f) + EPS);
; #pragma unroll
;           for (int mi = 0; mi < 4; ++mi) { const int ch = h * 64 + mi * 16 + 4 * q; const f32x4 gt = bf4_to_f32(gr[mi]);
;               const f32x4 gg = *(const f32x4*)(P.ret_g + ch), bb = *(const f32x4*)(P.ret_b + ch); const f32x4 y = o[mi] * rs * gg + bb;
.LBB0_1568:
	s_lshl_b32 s34, s34, 1
	v_add_u32_e32 v91, s34, v0
	v_add_u32_e32 v96, s34, v89
	ds_read_b128 v[92:95], v91 offset:54272
	ds_read_b128 v[96:99], v96
	s_mov_b32 s34, 32
	s_and_b64 vcc, exec, s[2:3]
	s_mov_b64 s[2:3], 0
	s_waitcnt lgkmcnt(0)
	v_mfma_f32_16x16x32_bf16 v[74:77], v[92:95], v[96:99], v[74:77]
	ds_read_b128 v[92:95], v91 offset:56576
	s_waitcnt lgkmcnt(0)
	v_mfma_f32_16x16x32_bf16 v[70:73], v[92:95], v[96:99], v[70:73]
	ds_read_b128 v[92:95], v91 offset:58880
	s_waitcnt lgkmcnt(0)
	v_mfma_f32_16x16x32_bf16 v[66:69], v[92:95], v[96:99], v[66:69]
	ds_read_b128 v[92:95], v91 offset:61184
	s_waitcnt lgkmcnt(0)
	v_mfma_f32_16x16x32_bf16 v[62:65], v[92:95], v[96:99], v[62:65]
	s_cbranch_vccnz .LBB0_1568
	v_or_b32_e32 v91, s1, v88
	v_add_u32_e32 v0, 1, v91
	v_cvt_f32_u32_e32 v0, v0
	s_mov_b64 s[2:3], 0x12800400
	s_add_i32 s29, s29, 1
	s_cmp_lg_u32 s29, 4
	v_mul_f32_e32 v0, v90, v0
	v_mul_f32_e32 v0, 0x3fb8aa3b, v0
	v_exp_f32_e32 v0, v0
	s_nop 0
	v_pk_fma_f32 v[76:77], v[0:1], v[76:77], v[60:61] op_sel_hi:[0,1,1]
	v_pk_fma_f32 v[74:75], v[0:1], v[74:75], v[58:59] op_sel_hi:[0,1,1]
	v_pk_mov_b32 v[58:59], v[74:75], v[76:77] op_sel:[1,0]
	v_mov_b32_e32 v60, v74
	v_mov_b32_e32 v61, v77
	v_pk_fma_f32 v[72:73], v[0:1], v[72:73], v[56:57] op_sel_hi:[0,1,1]
	v_pk_fma_f32 v[70:71], v[0:1], v[70:71], v[54:55] op_sel_hi:[0,1,1]
	v_pk_add_f32 v[58:59], v[58:59], v[60:61]
	v_pk_mov_b32 v[54:55], v[70:71], v[72:73] op_sel:[1,0]
	v_mov_b32_e32 v56, v70
	v_mov_b32_e32 v57, v73
	v_add_f32_e32 v58, v58, v59
	v_pk_add_f32 v[54:55], v[54:55], v[56:57]
	v_add_f32_e32 v88, 0, v58
	v_pk_add_f32 v[54:55], v[54:55], v[54:55] op_sel:[0,1] op_sel_hi:[1,0]
	v_pk_fma_f32 v[58:59], v[0:1], v[68:69], v[52:53] op_sel_hi:[0,1,1]
	v_pk_fma_f32 v[60:61], v[0:1], v[66:67], v[50:51] op_sel_hi:[0,1,1]
	v_pk_fma_f32 v[50:51], v[0:1], v[64:65], v[48:49] op_sel_hi:[0,1,1]
	v_pk_fma_f32 v[52:53], v[0:1], v[62:63], v[46:47] op_sel_hi:[0,1,1]
	v_add_f32_e32 v56, v60, v61
	v_add_f32_e32 v66, v58, v59
	v_mov_b32_e32 v89, v52
	v_mov_b32_e32 v55, v53
	v_mov_b32_e32 v57, v50
	v_mov_b32_e32 v67, v51
	v_pk_add_f32 v[46:47], v[88:89], v[54:55]
	v_pk_add_f32 v[48:49], v[56:57], v[66:67]
	s_nop 0
	v_pk_add_f32 v[46:47], v[46:47], v[48:49]
	s_nop 0
	v_add_f32_e32 v0, v46, v47
	v_lshlrev_b32_e32 v46, 2, v86
	v_bitop3_b32 v62, v46, 64, v210 bitop3:0x6c
	ds_bpermute_b32 v47, v62, v0
	v_bitop3_b32 v63, v46, s60, v210 bitop3:0x6c
	s_waitcnt lgkmcnt(0)
	v_add_f32_e32 v0, v0, v47
	ds_bpermute_b32 v46, v63, v0
	s_waitcnt lgkmcnt(0)
	v_add_f32_e32 v64, v0, v46
	v_fmamk_f32 v75, v64, 0xbc800000, v75
	v_fmac_f32_e32 v74, 0xbc800000, v64
	v_fmamk_f32 v77, v64, 0xbc800000, v77
	v_fmac_f32_e32 v76, 0xbc800000, v64
	v_pk_mul_f32 v[46:47], v[76:77], v[76:77]
	v_pk_mul_f32 v[48:49], v[74:75], v[74:75]
	v_fmamk_f32 v71, v64, 0xbc800000, v71
	v_pk_mov_b32 v[54:55], v[48:49], v[46:47] op_sel:[1,0]
	v_mov_b32_e32 v49, v47
	v_fmac_f32_e32 v70, 0xbc800000, v64
	v_fmamk_f32 v73, v64, 0xbc800000, v73
	v_fmac_f32_e32 v72, 0xbc800000, v64
	v_pk_add_f32 v[46:47], v[54:55], v[48:49]
	v_pk_mul_f32 v[48:49], v[72:73], v[72:73]
	v_pk_mul_f32 v[54:55], v[70:71], v[70:71]
	v_fmac_f32_e32 v60, 0xbc800000, v64
	v_pk_mov_b32 v[56:57], v[54:55], v[48:49] op_sel:[1,0]
	v_mov_b32_e32 v55, v49
	v_fmamk_f32 v61, v64, 0xbc800000, v61
	v_fmac_f32_e32 v58, 0xbc800000, v64
	v_mul_f32_e32 v0, v60, v60
	v_pk_add_f32 v[48:49], v[56:57], v[54:55]
	v_fmamk_f32 v59, v64, 0xbc800000, v59
	v_pk_fma_f32 v[54:55], v[60:61], v[60:61], v[0:1] op_sel_hi:[1,1,0]
	v_mul_f32_e32 v0, v58, v58
	v_pk_add_f32 v[46:47], v[46:47], v[46:47] op_sel_hi:[0,1]
	v_pk_add_f32 v[48:49], v[48:49], v[48:49] op_sel_hi:[0,1]
	v_pk_fma_f32 v[56:57], v[58:59], v[58:59], v[0:1] op_sel_hi:[1,1,0]
	v_fmamk_f32 v51, v64, 0xbc800000, v51
	v_fmac_f32_e32 v50, 0xbc800000, v64
	v_fmamk_f32 v53, v64, 0xbc800000, v53
	v_fmac_f32_e32 v52, 0xbc800000, v64
	v_mul_f32_e32 v54, v52, v52
	v_mul_f32_e32 v56, v53, v53
	v_mul_f32_e32 v46, v50, v50
	v_mul_f32_e32 v48, v51, v51
	v_pk_add_f32 v[54:55], v[54:55], v[56:57]
	v_pk_add_f32 v[46:47], v[46:47], v[48:49]
	s_nop 0
	v_pk_add_f32 v[46:47], v[54:55], v[46:47]
	s_nop 0
	v_add_f32_e32 v0, v46, v47
	ds_bpermute_b32 v46, v62, v0
	s_waitcnt lgkmcnt(0)
	v_add_f32_e32 v0, v0, v46
	ds_bpermute_b32 v46, v63, v0
	s_waitcnt lgkmcnt(0)
	v_add_f32_e32 v0, v0, v46
	v_fmamk_f32 v0, v0, 0x3c800000, v202
	v_add_u32_e32 v46, s28, v91
	v_rsq_f32_e32 v54, v0
	v_or_b32_e32 v0, s15, v87
	v_ashrrev_i32_e32 v47, 31, v46
	v_lshlrev_b64 v[46:47], 11, v[46:47]
	v_lshlrev_b64 v[64:65], 2, v[0:1]
	v_lshl_add_u64 v[46:47], s[18:19], 0, v[46:47]
	v_lshl_add_u64 v[62:63], s[20:21], 0, v[64:65]
	v_lshl_add_u64 v[64:65], s[22:23], 0, v[64:65]
	v_lshl_add_u64 v[56:57], v[46:47], 0, s[2:3]
	global_load_dwordx4 v[46:49], v[62:63], off
	global_load_dwordx4 v[66:69], v[64:65], off
	global_load_dwordx4 v[108:111], v[62:63], off offset:64
	global_load_dwordx4 v[112:115], v[64:65], off offset:64
	global_load_dwordx4 v[116:119], v[62:63], off offset:128
	global_load_dwordx4 v[120:123], v[64:65], off offset:128
	global_load_dwordx4 v[124:127], v[62:63], off offset:192
	global_load_dwordx4 v[128:131], v[64:65], off offset:192
	v_pk_mul_f32 v[74:75], v[74:75], v[54:55] op_sel_hi:[1,0]
	v_pk_mul_f32 v[76:77], v[76:77], v[54:55] op_sel_hi:[1,0]
	v_lshlrev_b32_e32 v0, 1, v0
	s_waitcnt vmcnt(0)
; DI unsigned pk2(float lo, float hi) { const f32x2 v = {lo, hi}; const hwbf16x2 b = __builtin_convertvector(v, hwbf16x2); return __builtin_bit_cast(unsigned, b); }
; DI float silu_f(float x) { return x * __builtin_amdgcn_rcpf(1.0f + __expf(-x)); }
; DI f32x4 bf4_to_f32(const u32x2 v) { return (f32x4){__uint_as_float(v.x << 16), __uint_as_float(v.x & 0xffff0000u), __uint_as_float(v.y << 16), __uint_as_float(v.y & 0xffff0000u)}; }
; DI void ret_pass2(LAS unsigned char* lds, const Args& a, const LayerP& P, int unit, int wv) {
;     ...
; #pragma unroll
;           for (int mi = 0; mi < 4; ++mi) { const int ch = h * 64 + mi * 16 + 4 * q; const f32x4 gt = bf4_to_f32(gr[mi]);
;               const f32x4 gg = *(const f32x4*)(P.ret_g + ch), bb = *(const f32x4*)(P.ret_b + ch); const f32x4 y = o[mi] * rs * gg + bb;
;               u32x2 w; w.x = pk2(silu_f(gt[0]) * y[0], silu_f(gt[1]) * y[1]); w.y = pk2(silu_f(gt[2]) * y[2], silu_f(gt[3]) * y[3]);
;               *(u32x2*)(Y + (size_t)(row0 + i) * DMODEL + 512 + ch) = w; } }
	v_pk_fma_f32 v[46:47], v[46:47], v[74:75], v[66:67]
	v_lshlrev_b32_e32 v66, 16, v84
	v_mul_f32_e32 v55, 0xbfb8aa3b, v66
	v_exp_f32_e32 v55, v55
	v_and_b32_e32 v67, 0xffff0000, v84
	v_pk_fma_f32 v[48:49], v[48:49], v[76:77], v[68:69]
	v_add_f32_e32 v55, 1.0, v55
	v_rcp_f32_e32 v68, v55
	v_mul_f32_e32 v55, 0xbfb8aa3b, v67
	v_exp_f32_e32 v55, v55
	s_nop 0
	v_add_f32_e32 v55, 1.0, v55
	v_rcp_f32_e32 v69, v55
	v_pk_mul_f32 v[70:71], v[70:71], v[54:55] op_sel_hi:[1,0]
	v_pk_mul_f32 v[72:73], v[72:73], v[54:55] op_sel_hi:[1,0]
	v_pk_mul_f32 v[66:67], v[68:69], v[66:67]
	s_nop 0
	v_pk_mul_f32 v[46:47], v[66:67], v[46:47]
	v_lshlrev_b32_e32 v66, 16, v85
	v_cvt_pk_bf16_f32 v46, v46, v47
	v_mul_f32_e32 v47, 0xbfb8aa3b, v66
	v_exp_f32_e32 v47, v47
	v_and_b32_e32 v67, 0xffff0000, v85
	v_add_f32_e32 v47, 1.0, v47
	v_rcp_f32_e32 v68, v47
	v_mul_f32_e32 v47, 0xbfb8aa3b, v67
	v_exp_f32_e32 v47, v47
	s_nop 0
	v_add_f32_e32 v47, 1.0, v47
	v_rcp_f32_e32 v69, v47
	s_nop 0
	v_pk_mul_f32 v[66:67], v[68:69], v[66:67]
	s_nop 0
	v_pk_mul_f32 v[48:49], v[66:67], v[48:49]
	s_nop 0
	v_cvt_pk_bf16_f32 v47, v48, v49
	v_lshl_add_u64 v[48:49], v[56:57], 0, v[0:1]
	global_store_dwordx2 v[48:49], v[46:47], off
	v_mov_b32_e32 v46, v108
	v_mov_b32_e32 v47, v109
	v_mov_b32_e32 v48, v110
	v_mov_b32_e32 v49, v111
	s_nop 0
	v_mov_b32_e32 v66, v112
	v_mov_b32_e32 v67, v113
	v_mov_b32_e32 v68, v114
	v_mov_b32_e32 v69, v115
	s_nop 0
	v_pk_fma_f32 v[46:47], v[46:47], v[70:71], v[66:67]
	v_lshlrev_b32_e32 v66, 16, v82
	v_mul_f32_e32 v55, 0xbfb8aa3b, v66
	v_exp_f32_e32 v55, v55
	v_and_b32_e32 v67, 0xffff0000, v82
	v_pk_fma_f32 v[48:49], v[48:49], v[72:73], v[68:69]
	v_add_f32_e32 v55, 1.0, v55
	v_rcp_f32_e32 v68, v55
	v_mul_f32_e32 v55, 0xbfb8aa3b, v67
	v_exp_f32_e32 v55, v55
	s_nop 0
	v_add_f32_e32 v55, 1.0, v55
	v_rcp_f32_e32 v69, v55
	v_pk_mul_f32 v[58:59], v[58:59], v[54:55] op_sel_hi:[1,0]
	v_pk_mul_f32 v[60:61], v[60:61], v[54:55] op_sel_hi:[1,0]
	v_pk_mul_f32 v[66:67], v[68:69], v[66:67]
	s_nop 0
	v_pk_mul_f32 v[46:47], v[66:67], v[46:47]
	v_lshlrev_b32_e32 v66, 16, v83
	v_cvt_pk_bf16_f32 v46, v46, v47
	v_mul_f32_e32 v47, 0xbfb8aa3b, v66
	v_exp_f32_e32 v47, v47
	v_and_b32_e32 v67, 0xffff0000, v83
	v_add_f32_e32 v47, 1.0, v47
	v_rcp_f32_e32 v68, v47
	v_mul_f32_e32 v47, 0xbfb8aa3b, v67
	v_exp_f32_e32 v47, v47
	s_nop 0
	v_add_f32_e32 v47, 1.0, v47
	v_rcp_f32_e32 v69, v47
	s_nop 0
	v_pk_mul_f32 v[66:67], v[68:69], v[66:67]
	s_nop 0
	v_pk_mul_f32 v[48:49], v[66:67], v[48:49]
	s_nop 0
	v_cvt_pk_bf16_f32 v47, v48, v49
	v_or_b32_e32 v48, 32, v0
	v_mov_b32_e32 v49, v1
	v_lshl_add_u64 v[48:49], v[56:57], 0, v[48:49]
	global_store_dwordx2 v[48:49], v[46:47], off
	v_mov_b32_e32 v46, v116
	v_mov_b32_e32 v47, v117
	v_mov_b32_e32 v48, v118
	v_mov_b32_e32 v49, v119
	s_nop 0
	v_mov_b32_e32 v66, v120
	v_mov_b32_e32 v67, v121
	v_mov_b32_e32 v68, v122
	v_mov_b32_e32 v69, v123
	s_nop 0
	v_pk_fma_f32 v[48:49], v[48:49], v[58:59], v[68:69]
	v_lshlrev_b32_e32 v58, 16, v80
	v_mul_f32_e32 v55, 0xbfb8aa3b, v58
	v_exp_f32_e32 v55, v55
	v_and_b32_e32 v59, 0xffff0000, v80
	v_pk_fma_f32 v[46:47], v[46:47], v[60:61], v[66:67]
	v_add_f32_e32 v55, 1.0, v55
	v_rcp_f32_e32 v60, v55
	v_mul_f32_e32 v55, 0xbfb8aa3b, v59
	v_exp_f32_e32 v55, v55
	s_nop 0
	v_add_f32_e32 v55, 1.0, v55
	v_rcp_f32_e32 v61, v55
	v_pk_mul_f32 v[50:51], v[50:51], v[54:55] op_sel_hi:[1,0]
	v_pk_mul_f32 v[52:53], v[52:53], v[54:55] op_sel_hi:[1,0]
	v_pk_mul_f32 v[58:59], v[60:61], v[58:59]
	s_nop 0
	v_pk_mul_f32 v[46:47], v[58:59], v[46:47]
	v_lshlrev_b32_e32 v58, 16, v81
	v_cvt_pk_bf16_f32 v46, v46, v47
	v_mul_f32_e32 v47, 0xbfb8aa3b, v58
	v_exp_f32_e32 v47, v47
	v_and_b32_e32 v59, 0xffff0000, v81
	v_add_f32_e32 v47, 1.0, v47
	v_rcp_f32_e32 v60, v47
	v_mul_f32_e32 v47, 0xbfb8aa3b, v59
	v_exp_f32_e32 v47, v47
	s_nop 0
	v_add_f32_e32 v47, 1.0, v47
	v_rcp_f32_e32 v61, v47
	s_nop 0
	v_pk_mul_f32 v[58:59], v[60:61], v[58:59]
	s_nop 0
	v_pk_mul_f32 v[48:49], v[58:59], v[48:49]
	s_nop 0
	v_cvt_pk_bf16_f32 v47, v48, v49
	v_or_b32_e32 v48, 64, v0
	v_mov_b32_e32 v49, v1
	v_lshl_add_u64 v[48:49], v[56:57], 0, v[48:49]
	global_store_dwordx2 v[48:49], v[46:47], off
	v_mov_b32_e32 v46, v124
	v_mov_b32_e32 v47, v125
	v_mov_b32_e32 v48, v126
	v_mov_b32_e32 v49, v127
	s_nop 0
	v_mov_b32_e32 v58, v128
	v_mov_b32_e32 v59, v129
	v_mov_b32_e32 v60, v130
	v_mov_b32_e32 v61, v131
	v_or_b32_e32 v0, 0x60, v0
	s_nop 0
	v_pk_fma_f32 v[48:49], v[48:49], v[50:51], v[60:61]
	v_lshlrev_b32_e32 v50, 16, v78
	v_and_b32_e32 v51, 0xffff0000, v78
	v_pk_fma_f32 v[46:47], v[46:47], v[52:53], v[58:59]
	v_mul_f32_e32 v52, 0xbfb8aa3b, v50
	v_mul_f32_e32 v53, 0xbfb8aa3b, v51
	v_exp_f32_e32 v52, v52
	v_exp_f32_e32 v53, v53
	v_add_f32_e32 v52, 1.0, v52
	v_add_f32_e32 v53, 1.0, v53
	v_rcp_f32_e32 v52, v52
	v_rcp_f32_e32 v53, v53
	s_nop 0
	v_pk_mul_f32 v[50:51], v[52:53], v[50:51]
	s_nop 0
	v_pk_mul_f32 v[46:47], v[50:51], v[46:47]
	v_lshlrev_b32_e32 v50, 16, v79
	v_cvt_pk_bf16_f32 v46, v46, v47
	v_mul_f32_e32 v47, 0xbfb8aa3b, v50
	v_exp_f32_e32 v47, v47
	v_and_b32_e32 v51, 0xffff0000, v79
	v_add_f32_e32 v47, 1.0, v47
	v_rcp_f32_e32 v52, v47
	v_mul_f32_e32 v47, 0xbfb8aa3b, v51
	v_exp_f32_e32 v47, v47
	s_nop 0
	v_add_f32_e32 v47, 1.0, v47
	v_rcp_f32_e32 v53, v47
	s_nop 0
	v_pk_mul_f32 v[50:51], v[52:53], v[50:51]
	s_nop 0
	v_pk_mul_f32 v[48:49], v[50:51], v[48:49]
	s_nop 0
	v_cvt_pk_bf16_f32 v47, v48, v49
	v_lshl_add_u64 v[48:49], v[56:57], 0, v[0:1]
	global_store_dwordx2 v[48:49], v[46:47], off
	s_cbranch_scc1 .LBB0_1497
	s_add_i32 s7, s7, s12
	s_cmpk_gt_i32 s7, 0xff
	s_cbranch_scc0 .LBB0_1496
